# attention: importance cross-half exchange via v_permlane32_swap (8 serial ds_bpermute round trips per compress tile removed); tile-list OR reduction via DPP/permlane
# baseline (speedup 1.0000x reference)
; #define LAS __attribute__((address_space(3)))
; DI unsigned pk2(float lo, float hi) { f32x2_t v = {lo, hi}; bf16x2_t b = __builtin_convertvector(v, bf16x2_t); return __builtin_bit_cast(unsigned, b); }
; DI void attn_tile(LAS const unsigned char* Ks, LAS const unsigned char* VT, const bf16x8 (&qf)[4], int ql, int hi,
;                   bool need_mask, bool col_en, int lo_b, int hi_b, float& m_ref, float& l_run, f32x16 (&o)[2], f32x16 (&sp)[2]) {
;     ...
;     for (int r = 0; r < 16; ++r) { const float e0 = fast_exp2(sp[0][r]), e1 = fast_exp2(sp[1][r]); sp[0][r] = e0; sp[1][r] = e1; ps += (f32x2_t){e0, e1}; }
;     l_run += ps[0] + ps[1];
;     bf16x8 pk[2][2];
; #pragma unroll
;     for (int p = 0; p < 2; ++p)
; #pragma unroll
;         for (int s = 0; s < 2; ++s) { u32x4 w; w.x = pk2(sp[p][8 * s], sp[p][8 * s + 1]); w.y = pk2(sp[p][8 * s + 2], sp[p][8 * s + 3]); w.z = pk2(sp[p][8 * s + 4], sp[p][8 * s + 5]); w.w = pk2(sp[p][8 * s + 6], sp[p][8 * s + 7]); pk[p][s] = __builtin_bit_cast(bf16x8, w); }
;     LAS const unsigned char* vb = VT + ((lane_ >> 4) & 1) * 32 + (lane_ & 3) * 8 + (4 * hi + ((lane_ & 15) >> 2)) * 64;
; #pragma unroll
;     for (int dh = 0; dh < 2; ++dh) {
;         bf16x8 vf[4];
; #pragma unroll
;         for (int ks = 0; ks < 4; ++ks) {
;             const s16x4 lo = __builtin_bit_cast(s16x4, __builtin_amdgcn_ds_read_tr16_b64_v4i16((LAS v4i16_t*)(vb + dh * 4096 + ks * 1024)));
;             const s16x4 hh = __builtin_bit_cast(s16x4, __builtin_amdgcn_ds_read_tr16_b64_v4i16((LAS v4i16_t*)(vb + dh * 4096 + ks * 1024 + 512)));
;             vf[ks] = (bf16x8){lo[0], lo[1], lo[2], lo[3], hh[0], hh[1], hh[2], hh[3]};
;         }
; #pragma unroll
;         for (int ks = 0; ks < 4; ++ks) o[dh] = MFMA32(vf[ks], pk[ks >> 1][ks & 1], o[dh]);
;     }
; DI void attn_unit(LAS unsigned char* lds, const Args& a, int bg, int qt) {
;     ...
;             if (two_cmp)
; #pragma unroll
;             for (int kk = 0; kk < 8; ++kk) { const int p = kk >> 2, k = kk & 3;
;                 const float xk = __shfl_xor(sp[p][4 * k + 3], 32);
;                 const float e4 = (sp[p][4 * k] + sp[p][4 * k + 1]) + (sp[p][4 * k + 2] + sp[p][4 * k + 3]);
;                 ip[16 * ct + 2 * kk + hi] = e4 + (hi ? xk : prev);
;                 prev = xk; asm volatile("" : "+v"(prev)); }
;             if (ct == 0) xcross = prev;
.LBB0_746:
	v_exp_f32_e32 v94, v43
	v_exp_f32_e32 v92, v42
	v_exp_f32_e32 v90, v40
	v_exp_f32_e32 v88, v41
	v_exp_f32_e32 v86, v38
	v_exp_f32_e32 v84, v39
	v_exp_f32_e32 v82, v36
	v_exp_f32_e32 v64, v37
	v_exp_f32_e32 v93, v31
	v_exp_f32_e32 v91, v33
	v_exp_f32_e32 v89, v30
	v_exp_f32_e32 v87, v32
	v_exp_f32_e32 v58, v22
	v_exp_f32_e32 v56, v23
	v_exp_f32_e32 v54, v20
	v_exp_f32_e32 v52, v21
	ds_read_b64_tr_b16 v[20:21], v238 offset:8192
	ds_read_b64_tr_b16 v[22:23], v238 offset:8704
	ds_read_b64_tr_b16 v[30:31], v238 offset:9216
	ds_read_b64_tr_b16 v[32:33], v238 offset:9728
	v_exp_f32_e32 v95, v35
	v_cvt_pk_bf16_f32 v152, v94, v92
	v_cvt_pk_bf16_f32 v153, v90, v88
	v_cvt_pk_bf16_f32 v154, v86, v84
	v_cvt_pk_bf16_f32 v155, v82, v64
	v_mov_b32_e32 v35, v34
	v_mov_b32_e32 v36, v34
	v_mov_b32_e32 v37, v34
	v_mov_b32_e32 v38, v34
	v_mov_b32_e32 v39, v34
	v_mov_b32_e32 v40, v34
	v_mov_b32_e32 v41, v34
	v_mov_b32_e32 v42, v34
	v_mov_b32_e32 v43, v34
	v_mov_b32_e32 v44, v34
	v_mov_b32_e32 v45, v34
	v_mov_b32_e32 v46, v34
	v_mov_b32_e32 v47, v34
	v_mov_b32_e32 v48, v34
	v_mov_b32_e32 v49, v34
	v_exp_f32_e32 v85, v5
	v_exp_f32_e32 v83, v8
	v_exp_f32_e32 v65, v4
	v_exp_f32_e32 v63, v7
	v_exp_f32_e32 v61, v3
	v_exp_f32_e32 v59, v6
	v_exp_f32_e32 v57, v2
	s_waitcnt lgkmcnt(2)
	v_mfma_f32_32x32x16_bf16 v[2:17], v[20:23], v[152:155], v[34:49]
	v_exp_f32_e32 v62, v24
	v_exp_f32_e32 v60, v25
	v_exp_f32_e32 v50, v18
	v_exp_f32_e32 v96, v19
	v_cvt_pk_bf16_f32 v157, v58, v56
	v_cvt_pk_bf16_f32 v156, v62, v60
	v_cvt_pk_bf16_f32 v158, v54, v52
	v_cvt_pk_bf16_f32 v159, v50, v96
	ds_read_b64_tr_b16 v[18:19], v238 offset:10240
	ds_read_b64_tr_b16 v[20:21], v238 offset:10752
	s_waitcnt lgkmcnt(2)
	v_mfma_f32_32x32x16_bf16 v[2:17], v[30:33], v[156:159], v[2:17]
	v_cvt_pk_bf16_f32 v160, v95, v93
	v_cvt_pk_bf16_f32 v161, v91, v89
	v_cvt_pk_bf16_f32 v162, v87, v85
	v_cvt_pk_bf16_f32 v163, v83, v65
	v_exp_f32_e32 v55, v29
	ds_read_b64_tr_b16 v[22:23], v238 offset:11264
	ds_read_b64_tr_b16 v[24:25], v238 offset:11776
	v_exp_f32_e32 v53, v26
	s_waitcnt lgkmcnt(2)
	v_mfma_f32_32x32x16_bf16 v[2:17], v[18:21], v[160:163], v[2:17]
	v_exp_f32_e32 v51, v28
	v_exp_f32_e32 v97, v27
	v_cvt_pk_bf16_f32 v164, v63, v61
	v_cvt_pk_bf16_f32 v165, v59, v57
	v_cvt_pk_bf16_f32 v166, v55, v53
	v_cvt_pk_bf16_f32 v167, v51, v97
	ds_read_b64_tr_b16 v[168:169], v238 offset:12288
	ds_read_b64_tr_b16 v[170:171], v238 offset:12800
	ds_read_b64_tr_b16 v[172:173], v238 offset:13312
	ds_read_b64_tr_b16 v[174:175], v238 offset:13824
	s_waitcnt lgkmcnt(4)
	v_mfma_f32_32x32x16_bf16 v[2:17], v[22:25], v[164:167], v[2:17]
	v_mov_b64_e32 v[18:19], v[34:35]
	v_mov_b64_e32 v[20:21], v[36:37]
	v_mov_b64_e32 v[22:23], v[38:39]
	v_mov_b64_e32 v[24:25], v[40:41]
	v_mov_b64_e32 v[26:27], v[42:43]
	v_mov_b64_e32 v[28:29], v[44:45]
	v_mov_b64_e32 v[30:31], v[46:47]
	v_mov_b64_e32 v[32:33], v[48:49]
	ds_read_b64_tr_b16 v[36:37], v238 offset:14336
	ds_read_b64_tr_b16 v[38:39], v238 offset:14848
	ds_read_b64_tr_b16 v[40:41], v238 offset:15360
	ds_read_b64_tr_b16 v[42:43], v238 offset:15872
	s_waitcnt lgkmcnt(6)
	v_mfma_f32_32x32x16_bf16 v[18:33], v[168:171], v[152:155], v[18:33]
	v_lshl_or_b32 v141, s28, 6, v139
	v_mul_lo_u32 v35, v141, s60
	s_lshl_b32 s76, s29, 6
	v_mov_b32_e32 v143, 0
	s_andn2_b64 vcc, exec, s[12:13]
	v_add_u32_e32 v145, v186, v35
	s_waitcnt lgkmcnt(4)
	v_mfma_f32_32x32x16_bf16 v[18:33], v[172:175], v[156:159], v[18:33]
	s_waitcnt lgkmcnt(2)
	v_mfma_f32_32x32x16_bf16 v[18:33], v[36:39], v[160:163], v[18:33]
	v_cndmask_b32_e64 v36, 0, 1, s[12:13]
	v_cmp_ne_u32_e64 s[8:9], 1, v36
	s_waitcnt lgkmcnt(0)
	v_mfma_f32_32x32x16_bf16 v[18:33], v[40:43], v[164:167], v[18:33]
	s_cbranch_vccnz .LBB0_748
	v_mov_b32_e32 v36, 0
	v_mov_b32_e32 v37, v88
	v_add_f32_e32 v38, v94, v92
	v_add_f32_e32 v39, v90, v88
	v_permlane32_swap_b32_e32 v36, v37
	v_add_f32_e32 v38, v38, v39
	v_add_f32_e32 v38, v38, v36
	ds_write_b32 v145, v38
	v_mov_b32_e32 v36, v88
	v_mov_b32_e32 v37, v64
	v_add_f32_e32 v38, v86, v84
	v_add_f32_e32 v39, v82, v64
	v_permlane32_swap_b32_e32 v36, v37
	v_add_f32_e32 v38, v38, v39
	v_cndmask_b32_e64 v36, v36, v37, s[42:43]
	v_add_f32_e32 v38, v38, v36
	ds_write_b32 v145, v38 offset:8
	v_mov_b32_e32 v36, v64
	v_mov_b32_e32 v37, v56
	v_add_f32_e32 v38, v62, v60
	v_add_f32_e32 v39, v58, v56
	v_permlane32_swap_b32_e32 v36, v37
	v_add_f32_e32 v38, v38, v39
	v_cndmask_b32_e64 v36, v36, v37, s[42:43]
	v_add_f32_e32 v38, v38, v36
	ds_write_b32 v145, v38 offset:16
	v_mov_b32_e32 v36, v56
	v_mov_b32_e32 v37, v96
	v_add_f32_e32 v38, v54, v52
	v_add_f32_e32 v39, v50, v96
	v_permlane32_swap_b32_e32 v36, v37
	v_add_f32_e32 v38, v38, v39
	v_cndmask_b32_e64 v36, v36, v37, s[42:43]
	v_add_f32_e32 v38, v38, v36
	ds_write_b32 v145, v38 offset:24
	v_mov_b32_e32 v36, v96
	v_mov_b32_e32 v37, v89
	v_add_f32_e32 v38, v95, v93
	v_add_f32_e32 v39, v91, v89
	v_permlane32_swap_b32_e32 v36, v37
	v_add_f32_e32 v38, v38, v39
	v_cndmask_b32_e64 v36, v36, v37, s[42:43]
	v_add_f32_e32 v38, v38, v36
	ds_write_b32 v145, v38 offset:32
	v_mov_b32_e32 v36, v89
	v_mov_b32_e32 v37, v65
	v_add_f32_e32 v38, v87, v85
	v_add_f32_e32 v39, v83, v65
	v_permlane32_swap_b32_e32 v36, v37
	v_add_f32_e32 v38, v38, v39
	v_cndmask_b32_e64 v36, v36, v37, s[42:43]
	v_add_f32_e32 v38, v38, v36
	ds_write_b32 v145, v38 offset:40
	v_mov_b32_e32 v36, v65
	v_mov_b32_e32 v37, v57
	v_add_f32_e32 v38, v63, v61
	v_add_f32_e32 v39, v59, v57
	v_permlane32_swap_b32_e32 v36, v37
	v_add_f32_e32 v38, v38, v39
	v_cndmask_b32_e64 v36, v36, v37, s[42:43]
	v_add_f32_e32 v38, v38, v36
	ds_write_b32 v145, v38 offset:48
	v_mov_b32_e32 v36, v57
	v_mov_b32_e32 v37, v97
	v_add_f32_e32 v38, v55, v53
	v_add_f32_e32 v39, v51, v97
	v_permlane32_swap_b32_e32 v36, v37
	v_add_f32_e32 v38, v38, v39
	v_cndmask_b32_e64 v36, v36, v37, s[42:43]
	v_add_f32_e32 v38, v38, v36
	ds_write_b32 v145, v38 offset:56
	v_mov_b32_e32 v36, v97
	v_mov_b32_e32 v37, v97
	s_nop 1
	v_permlane32_swap_b32_e32 v36, v37
	v_cndmask_b32_e64 v143, v36, v37, s[42:43]

; #define LAS __attribute__((address_space(3)))
; DI unsigned pk2(float lo, float hi) { f32x2_t v = {lo, hi}; bf16x2_t b = __builtin_convertvector(v, bf16x2_t); return __builtin_bit_cast(unsigned, b); }
; DI float fast_exp2(float x) { return __builtin_amdgcn_exp2f(x); }
; DI void attn_tile(LAS const unsigned char* Ks, LAS const unsigned char* VT, const bf16x8 (&qf)[4], int ql, int hi,
;                   bool need_mask, bool col_en, int lo_b, int hi_b, float& m_ref, float& l_run, f32x16 (&o)[2], f32x16 (&sp)[2]) {
;     ...
;     for (int r = 0; r < 16; ++r) { const float e0 = fast_exp2(sp[0][r]), e1 = fast_exp2(sp[1][r]); sp[0][r] = e0; sp[1][r] = e1; ps += (f32x2_t){e0, e1}; }
;     l_run += ps[0] + ps[1];
;     bf16x8 pk[2][2];
; #pragma unroll
;     for (int p = 0; p < 2; ++p)
; #pragma unroll
;         for (int s = 0; s < 2; ++s) { u32x4 w; w.x = pk2(sp[p][8 * s], sp[p][8 * s + 1]); w.y = pk2(sp[p][8 * s + 2], sp[p][8 * s + 3]); w.z = pk2(sp[p][8 * s + 4], sp[p][8 * s + 5]); w.w = pk2(sp[p][8 * s + 6], sp[p][8 * s + 7]); pk[p][s] = __builtin_bit_cast(bf16x8, w); }
;     LAS const unsigned char* vb = VT + ((lane_ >> 4) & 1) * 32 + (lane_ & 3) * 8 + (4 * hi + ((lane_ & 15) >> 2)) * 64;
; #pragma unroll
;     for (int dh = 0; dh < 2; ++dh) {
;         bf16x8 vf[4];
; #pragma unroll
;         for (int ks = 0; ks < 4; ++ks) {
;             const s16x4 lo = __builtin_bit_cast(s16x4, __builtin_amdgcn_ds_read_tr16_b64_v4i16((LAS v4i16_t*)(vb + dh * 4096 + ks * 1024)));
;             const s16x4 hh = __builtin_bit_cast(s16x4, __builtin_amdgcn_ds_read_tr16_b64_v4i16((LAS v4i16_t*)(vb + dh * 4096 + ks * 1024 + 512)));
;             vf[ks] = (bf16x8){lo[0], lo[1], lo[2], lo[3], hh[0], hh[1], hh[2], hh[3]};
;         }
; #pragma unroll
;         for (int ks = 0; ks < 4; ++ks) o[dh] = MFMA32(vf[ks], pk[ks >> 1][ks & 1], o[dh]);
;     }
; DI void attn_unit(LAS unsigned char* lds, const Args& a, int bg, int qt) {
;     ...
;             if (two_cmp)
; #pragma unroll
;             for (int kk = 0; kk < 8; ++kk) { const int p = kk >> 2, k = kk & 3;
;                 const float xk = __shfl_xor(sp[p][4 * k + 3], 32);
;                 const float e4 = (sp[p][4 * k] + sp[p][4 * k + 1]) + (sp[p][4 * k + 2] + sp[p][4 * k + 3]);
;                 ip[16 * ct + 2 * kk + hi] = e4 + (hi ? xk : prev);
;                 prev = xk; asm volatile("" : "+v"(prev)); }
.LBB0_763:
	v_exp_f32_e32 v34, v89
	v_exp_f32_e32 v35, v35
	v_exp_f32_e32 v36, v88
	v_exp_f32_e32 v37, v96
	v_exp_f32_e32 v38, v86
	v_exp_f32_e32 v39, v97
	v_pk_add_f32 v[40:41], v[34:35], 0 op_sel_hi:[1,0]
	v_exp_f32_e32 v42, v87
	v_pk_add_f32 v[40:41], v[36:37], v[40:41]
	v_exp_f32_e32 v44, v85
	v_pk_add_f32 v[160:161], v[38:39], v[40:41]
	v_exp_f32_e32 v40, v84
	v_exp_f32_e32 v45, v58
	v_exp_f32_e32 v46, v82
	v_exp_f32_e32 v58, v83
	ds_read_b64_tr_b16 v[82:83], v238 offset:24576
	ds_read_b64_tr_b16 v[84:85], v238 offset:25088
	v_cvt_pk_bf16_f32 v86, v34, v36
	v_cvt_pk_bf16_f32 v87, v38, v42
	v_cvt_pk_bf16_f32 v88, v40, v44
	v_cvt_pk_bf16_f32 v89, v46, v58
	v_exp_f32_e32 v43, v94
	v_exp_f32_e32 v41, v95
	s_waitcnt lgkmcnt(0)
	v_mfma_f32_32x32x16_bf16 v[2:17], v[82:85], v[86:89], v[2:17]
	v_exp_f32_e32 v47, v93
	v_exp_f32_e32 v48, v56
	v_exp_f32_e32 v49, v62
	v_exp_f32_e32 v56, v57
	v_exp_f32_e32 v57, v60
	v_exp_f32_e32 v60, v54
	v_exp_f32_e32 v62, v55
	v_exp_f32_e32 v54, v52
	v_exp_f32_e32 v55, v92
	v_exp_f32_e32 v52, v53
	v_exp_f32_e32 v50, v50
	ds_read_b64_tr_b16 v[92:93], v238 offset:25600
	ds_read_b64_tr_b16 v[94:95], v238 offset:26112
	v_exp_f32_e32 v162, v51
	v_cvt_pk_bf16_f32 v82, v48, v56
	v_cvt_pk_bf16_f32 v83, v60, v62
	v_cvt_pk_bf16_f32 v84, v54, v52
	v_cvt_pk_bf16_f32 v85, v50, v162
	v_exp_f32_e32 v59, v59
	ds_read_b64_tr_b16 v[152:153], v238 offset:26624
	ds_read_b64_tr_b16 v[154:155], v238 offset:27136
	s_waitcnt lgkmcnt(2)
	v_mfma_f32_32x32x16_bf16 v[2:17], v[92:95], v[82:85], v[2:17]
	v_exp_f32_e32 v53, v91
	v_exp_f32_e32 v51, v90
	v_cvt_pk_bf16_f32 v90, v35, v37
	v_cvt_pk_bf16_f32 v91, v39, v43
	v_cvt_pk_bf16_f32 v92, v41, v45
	v_cvt_pk_bf16_f32 v93, v47, v59
	v_exp_f32_e32 v61, v61
	v_exp_f32_e32 v63, v63
	s_waitcnt lgkmcnt(0)
	v_mfma_f32_32x32x16_bf16 v[2:17], v[152:155], v[90:93], v[2:17]
	ds_read_b64_tr_b16 v[94:95], v238 offset:27648
	ds_read_b64_tr_b16 v[96:97], v238 offset:28160
	v_exp_f32_e32 v163, v65
	ds_read_b64_tr_b16 v[156:157], v238 offset:28672
	ds_read_b64_tr_b16 v[158:159], v238 offset:29184
	v_cvt_pk_bf16_f32 v152, v49, v57
	v_cvt_pk_bf16_f32 v153, v61, v63
	v_cvt_pk_bf16_f32 v154, v55, v53
	v_cvt_pk_bf16_f32 v155, v51, v163
	s_waitcnt lgkmcnt(0)
	v_mfma_f32_32x32x16_bf16 v[18:33], v[156:159], v[86:89], v[18:33]
	v_add_f32_e32 v34, v34, v36
	v_add_f32_e32 v36, v38, v42
	v_add_f32_e32 v34, v34, v36
	v_add_f32_e32 v38, v46, v58
	v_add_f32_e32 v35, v35, v37
	v_add_f32_e32 v37, v39, v43
	v_add_f32_e32 v35, v35, v37
	v_mfma_f32_32x32x16_bf16 v[2:17], v[94:97], v[152:155], v[2:17]
	v_add_f32_e64 v94, v42, v160
	v_add_f32_e64 v95, v43, v161
	v_add_f32_e32 v37, v47, v59
	v_add_f32_e64 v94, v40, v94
	v_add_f32_e64 v95, v41, v95
	s_mov_b64 s[10:11], s[42:43]
	v_pk_add_f32 v[94:95], v[44:45], v[94:95]
	s_nop 0
	v_pk_add_f32 v[94:95], v[46:47], v[94:95]
	s_nop 0
	v_pk_add_f32 v[160:161], v[58:59], v[94:95]
	ds_read_b64_tr_b16 v[94:95], v238 offset:29696
	ds_read_b64_tr_b16 v[96:97], v238 offset:30208
	v_pk_add_f32 v[86:87], v[48:49], v[160:161]
	s_waitcnt lgkmcnt(0)
	v_mfma_f32_32x32x16_bf16 v[18:33], v[94:97], v[82:85], v[18:33]
	v_add_f32_e64 v86, v56, v86
	v_add_f32_e64 v87, v57, v87
	v_add_f32_e64 v86, v60, v86
	v_add_f32_e64 v87, v61, v87
	v_add_f32_e64 v86, v62, v86
	v_add_f32_e64 v87, v63, v87
	v_pk_add_f32 v[156:157], v[54:55], v[86:87]
	ds_read_b64_tr_b16 v[86:87], v238 offset:30720
	ds_read_b64_tr_b16 v[88:89], v238 offset:31232
	v_pk_add_f32 v[82:83], v[52:53], v[156:157]
	s_waitcnt lgkmcnt(0)
	v_mfma_f32_32x32x16_bf16 v[18:33], v[86:89], v[90:93], v[18:33]
	v_add_f32_e64 v82, v50, v82
	v_add_f32_e64 v83, v51, v83
	v_and_b32_e32 v86, 64, v239
	v_add_f32_e64 v82, v162, v82
	v_add_f32_e64 v83, v163, v83
	v_add_u32_e32 v86, 64, v86
	v_add_f32_e32 v65, v82, v83
	v_add_f32_e32 v149, v149, v65
	v_xor_b32_e32 v65, 32, v239
	v_cmp_lt_i32_e32 vcc, v65, v86
	ds_read_b64_tr_b16 v[82:83], v238 offset:31744
	ds_read_b64_tr_b16 v[84:85], v238 offset:32256
	v_cndmask_b32_e32 v65, v239, v65, vcc
	v_lshlrev_b32_e32 v65, 2, v65
	s_waitcnt lgkmcnt(0)
	v_mfma_f32_32x32x16_bf16 v[18:33], v[82:85], v[152:155], v[18:33]
	v_mov_b32_e32 v65, 0
	v_mov_b32_e32 v86, v42
	s_nop 1
	v_permlane32_swap_b32_e32 v65, v86
	v_add_f32_e32 v34, v34, v65
	ds_write_b32 v145, v34 offset:64
	v_mov_b32_e32 v65, v42
	v_mov_b32_e32 v86, v58
	v_add_f32_e32 v36, v40, v44
	v_add_f32_e32 v36, v36, v38
	v_add_f32_e32 v40, v60, v62
	v_permlane32_swap_b32_e32 v65, v86
	v_cndmask_b32_e64 v38, v65, v86, s[42:43]
	v_add_f32_e32 v36, v36, v38
	ds_write_b32 v145, v36 offset:72
	v_mov_b32_e32 v65, v58
	v_mov_b32_e32 v86, v62
	v_add_f32_e32 v38, v48, v56
	v_add_f32_e32 v38, v38, v40
	v_add_f32_e32 v40, v50, v162
	v_permlane32_swap_b32_e32 v65, v86
	v_cndmask_b32_e64 v34, v65, v86, s[42:43]
	v_add_f32_e32 v34, v38, v34
	ds_write_b32 v145, v34 offset:80
	v_mov_b32_e32 v65, v62
	v_mov_b32_e32 v86, v162
	v_add_f32_e32 v38, v54, v52
	v_add_f32_e32 v38, v38, v40
	v_permlane32_swap_b32_e32 v65, v86
	v_cndmask_b32_e64 v36, v65, v86, s[42:43]
	v_add_f32_e32 v36, v38, v36
	ds_write_b32 v145, v36 offset:88
	v_mov_b32_e32 v65, v162
	v_mov_b32_e32 v86, v43
	s_nop 1
	v_permlane32_swap_b32_e32 v65, v86
	v_cndmask_b32_e64 v34, v65, v86, s[42:43]
	v_add_f32_e32 v34, v35, v34
	ds_write_b32 v145, v34 offset:96
	v_mov_b32_e32 v65, v43
	v_mov_b32_e32 v86, v59
	v_add_f32_e32 v35, v41, v45
	v_add_f32_e32 v35, v35, v37
	v_add_f32_e32 v37, v61, v63
	v_permlane32_swap_b32_e32 v65, v86
	v_cndmask_b32_e64 v36, v65, v86, s[42:43]
	v_add_f32_e32 v35, v35, v36
	ds_write_b32 v145, v35 offset:104
	v_mov_b32_e32 v65, v59
	v_mov_b32_e32 v86, v63
	v_add_f32_e32 v36, v49, v57
	v_add_f32_e32 v36, v36, v37
	v_add_f32_e32 v37, v51, v163
	v_permlane32_swap_b32_e32 v65, v86
	v_cndmask_b32_e64 v34, v65, v86, s[42:43]
	v_add_f32_e32 v34, v36, v34
	ds_write_b32 v145, v34 offset:112
	v_mov_b32_e32 v65, v63
	v_mov_b32_e32 v86, v163
	v_add_f32_e32 v36, v55, v53
	v_add_f32_e32 v36, v36, v37
	v_permlane32_swap_b32_e32 v65, v86
	v_cndmask_b32_e64 v35, v65, v86, s[42:43]
	v_add_f32_e32 v35, v36, v35
	ds_write_b32 v145, v35 offset:120
